# v11 + dilated attention: QK waits no longer drain the next tile's prefetch loads
# baseline (speedup 1.0000x reference)
; #define LAS __attribute__((address_space(3)))
; #define MFMA32(a, b, c) __builtin_amdgcn_mfma_f32_32x32x16_bf16((a), (b), (c), 0, 0, 0)
; template <int D, int NM, int KSTR, int VSTR, bool QLDS, class BF> ...
;     v8s P[NM][2];
; #pragma unroll
;     for (int m = 0; m < NM; ++m) {
;         const LAS unsigned char* Kb = (m == 0 ? K0 : K1) + (32 * kk + r) * KSTR + h * 16;
;         v16f S;
; #pragma unroll
;         for (int i = 0; i < 16; ++i) S[i] = 0.f;
;         v8s kfa[D / 16];
; #pragma unroll
;         for (int ks = 0; ks < D / 16; ++ks) kfa[ks] = *(const LAS v8s*)(Kb + ks * 32);
;         __builtin_amdgcn_sched_barrier(0);
; #pragma unroll
;         for (int ks = 0; ks < D / 16; ++ks) { const v8s qf = QLDS ? *(const LAS v8s*)(qlds + (m * (D / 16) + ks) * 1024) : Q[m][ks]; S = MFMA32(kfa[ks], qf, S); }
;         __builtin_amdgcn_sched_barrier(0);
;         float tmax = NEGBIG;
; #pragma unroll
;         for (int i = 0; i < 16; ++i) { S[i] = S[i] * c1 + bias(i); tmax = fmaxf(tmax, S[i]); }
; __device__ __forceinline__ void dil_item(const Params& p, LAS unsigned char* lds, const int bitem) {
;     ...
;             for (int kk = 0; kk < 2; ++kk) {
;                 const int js = j0 + 32 * kk;
;                 if (js + 31 >= jq0 - 64 && js <= jq0 + 31 + 64) {
;                     const BiasBand bf{tab, js + 4 * h - jq};
;                     attn_subtile<128, 1, 272, 320, false>(base + DL_K, base + DL_K, base + DL_VT, kk, Q, nullptr, st, c1, bf, r, h);
.LBB0_172:
	s_and_saveexec_b64 s[18:19], s[10:11]
	s_cbranch_execz .LBB0_165
	v_subrev_u32_e32 v67, 33, v176
	v_cmp_ge_i32_e32 vcc, v67, v188
	v_cmp_le_i32_e64 s[38:39], v66, v189
	s_and_b64 s[10:11], vcc, s[38:39]
	s_and_saveexec_b64 s[20:21], s[10:11]
	s_cbranch_execz .LBB0_209
	v_add_u32_e32 v70, v190, v187
	ds_read_b128 v[66:69], v70
	ds_read_b128 v[198:201], v70 offset:32
	ds_read_b128 v[216:219], v70 offset:64
	ds_read_b128 v[220:223], v70 offset:96
	ds_read_b128 v[224:227], v70 offset:128
	ds_read_b128 v[228:231], v70 offset:160
	ds_read_b128 v[232:235], v70 offset:192
	ds_read_b128 v[236:239], v70 offset:224
	v_lshl_add_u64 v[178:179], v[174:175], 0, s[6:7]
	v_subrev_u32_e32 v197, 64, v178
	s_waitcnt lgkmcnt(7)
	v_mfma_f32_32x32x16_bf16 v[66:81], v[66:69], v[82:85], 0
	s_waitcnt lgkmcnt(6)
	v_mfma_f32_32x32x16_bf16 v[66:81], v[198:201], v[86:89], v[66:81]
	s_waitcnt lgkmcnt(5)
	v_mfma_f32_32x32x16_bf16 v[66:81], v[216:219], v[90:93], v[66:81]
	s_waitcnt lgkmcnt(4)
	v_mfma_f32_32x32x16_bf16 v[66:81], v[220:223], v[94:97], v[66:81]
	s_waitcnt lgkmcnt(3)
	v_mfma_f32_32x32x16_bf16 v[66:81], v[224:227], v[98:101], v[66:81]
	s_waitcnt lgkmcnt(2)
	v_mfma_f32_32x32x16_bf16 v[66:81], v[228:231], v[102:105], v[66:81]
	s_waitcnt lgkmcnt(1)
	v_mfma_f32_32x32x16_bf16 v[66:81], v[232:235], v[106:109], v[66:81]
	s_waitcnt lgkmcnt(0)
	v_mfma_f32_32x32x16_bf16 v[66:81], v[236:239], v[110:113], v[66:81]
	v_sub_u32_e32 v177, 0, v197
	v_max_i32_e32 v177, v197, v177
	v_cmp_gt_u32_e32 vcc, s26, v177
	v_mov_b32_e32 v177, 0xf149f2ca
	v_mov_b32_e32 v179, 0xf149f2ca
	s_and_saveexec_b64 s[10:11], vcc
	v_med3_i32 v179, v197, s27, 64
	v_lshl_add_u32 v179, v179, 2, v147
	ds_read_b32 v179, v179 offset:256
	s_or_b64 exec, exec, s[10:11]
	v_subrev_u32_e32 v197, 63, v178
	v_sub_u32_e32 v198, 63, v178
	v_max_i32_e32 v198, v197, v198
	v_cmp_gt_u32_e32 vcc, s26, v198
	s_and_saveexec_b64 s[10:11], vcc
	v_med3_i32 v177, v197, s27, 64
	v_lshl_add_u32 v177, v177, 2, v147
	ds_read_b32 v177, v177 offset:256
	s_or_b64 exec, exec, s[10:11]
	v_subrev_u32_e32 v199, 62, v178
	v_sub_u32_e32 v197, 62, v178
	v_max_i32_e32 v197, v199, v197
	v_cmp_gt_u32_e32 vcc, s26, v197
	v_mov_b32_e32 v197, 0xf149f2ca
	v_mov_b32_e32 v198, 0xf149f2ca
	s_and_saveexec_b64 s[10:11], vcc
	v_med3_i32 v198, v199, s27, 64
	v_lshl_add_u32 v198, v198, 2, v147
	ds_read_b32 v198, v198 offset:256
	s_or_b64 exec, exec, s[10:11]
	v_subrev_u32_e32 v199, 61, v178
	v_sub_u32_e32 v200, 61, v178
	v_max_i32_e32 v200, v199, v200
	v_cmp_gt_u32_e32 vcc, s26, v200
	s_and_saveexec_b64 s[10:11], vcc
	v_med3_i32 v197, v199, s27, 64
	v_lshl_add_u32 v197, v197, 2, v147
	ds_read_b32 v197, v197 offset:256
	s_or_b64 exec, exec, s[10:11]
	v_subrev_u32_e32 v201, 56, v178
	v_sub_u32_e32 v199, 56, v178
	v_max_i32_e32 v199, v201, v199
	v_cmp_gt_u32_e32 vcc, s26, v199
	v_mov_b32_e32 v199, 0xf149f2ca
	v_mov_b32_e32 v200, 0xf149f2ca
	s_and_saveexec_b64 s[10:11], vcc
	v_med3_i32 v200, v201, s27, 64
	v_lshl_add_u32 v200, v200, 2, v147
	ds_read_b32 v200, v200 offset:256
	s_or_b64 exec, exec, s[10:11]
	v_subrev_u32_e32 v201, 55, v178
	v_sub_u32_e32 v202, 55, v178
	v_max_i32_e32 v202, v201, v202
	v_cmp_gt_u32_e32 vcc, s26, v202
	s_and_saveexec_b64 s[10:11], vcc
	v_med3_i32 v199, v201, s27, 64
	v_lshl_add_u32 v199, v199, 2, v147
	ds_read_b32 v199, v199 offset:256
	s_or_b64 exec, exec, s[10:11]
	v_subrev_u32_e32 v203, 54, v178
	v_sub_u32_e32 v201, 54, v178
	v_max_i32_e32 v201, v203, v201
	v_cmp_gt_u32_e32 vcc, s26, v201
	v_mov_b32_e32 v201, 0xf149f2ca
	v_mov_b32_e32 v202, 0xf149f2ca
	s_and_saveexec_b64 s[10:11], vcc
	v_med3_i32 v202, v203, s27, 64
	v_lshl_add_u32 v202, v202, 2, v147
	ds_read_b32 v202, v202 offset:256
	s_or_b64 exec, exec, s[10:11]
	v_subrev_u32_e32 v203, 53, v178
	v_sub_u32_e32 v215, 53, v178
	v_max_i32_e32 v215, v203, v215
	v_cmp_gt_u32_e32 vcc, s26, v215
	s_and_saveexec_b64 s[10:11], vcc
	v_med3_i32 v201, v203, s27, 64
	v_lshl_add_u32 v201, v201, 2, v147
	ds_read_b32 v201, v201 offset:256
	s_or_b64 exec, exec, s[10:11]
	v_subrev_u32_e32 v216, 48, v178
	v_sub_u32_e32 v203, 48, v178
	v_max_i32_e32 v203, v216, v203
	v_cmp_gt_u32_e32 vcc, s26, v203
	v_mov_b32_e32 v203, 0xf149f2ca
	v_mov_b32_e32 v215, 0xf149f2ca
	s_and_saveexec_b64 s[10:11], vcc
	v_med3_i32 v215, v216, s27, 64
	v_lshl_add_u32 v215, v215, 2, v147
	ds_read_b32 v215, v215 offset:256
	s_or_b64 exec, exec, s[10:11]
	v_subrev_u32_e32 v216, 47, v178
	v_sub_u32_e32 v217, 47, v178
	v_max_i32_e32 v217, v216, v217
	v_cmp_gt_u32_e32 vcc, s26, v217
	s_and_saveexec_b64 s[10:11], vcc
	v_med3_i32 v203, v216, s27, 64
	v_lshl_add_u32 v203, v203, 2, v147
	ds_read_b32 v203, v203 offset:256
	s_or_b64 exec, exec, s[10:11]
	v_subrev_u32_e32 v218, 46, v178
	v_sub_u32_e32 v216, 46, v178
	v_max_i32_e32 v216, v218, v216
	v_cmp_gt_u32_e32 vcc, s26, v216
	v_mov_b32_e32 v216, 0xf149f2ca
	v_mov_b32_e32 v217, 0xf149f2ca
	s_and_saveexec_b64 s[10:11], vcc
	v_med3_i32 v217, v218, s27, 64
	v_lshl_add_u32 v217, v217, 2, v147
	ds_read_b32 v217, v217 offset:256
	s_or_b64 exec, exec, s[10:11]
	v_subrev_u32_e32 v218, 45, v178
	v_sub_u32_e32 v219, 45, v178
	v_max_i32_e32 v219, v218, v219
	v_cmp_gt_u32_e32 vcc, s26, v219
	s_and_saveexec_b64 s[10:11], vcc
	v_med3_i32 v216, v218, s27, 64
	v_lshl_add_u32 v216, v216, 2, v147
	ds_read_b32 v216, v216 offset:256
	s_or_b64 exec, exec, s[10:11]
	v_subrev_u32_e32 v220, 40, v178
	v_sub_u32_e32 v218, 40, v178
	v_max_i32_e32 v218, v220, v218
	v_cmp_gt_u32_e32 vcc, s26, v218
	v_mov_b32_e32 v218, 0xf149f2ca
	v_mov_b32_e32 v219, 0xf149f2ca
	s_and_saveexec_b64 s[10:11], vcc
	v_med3_i32 v219, v220, s27, 64
	v_lshl_add_u32 v219, v219, 2, v147
	ds_read_b32 v219, v219 offset:256
	s_or_b64 exec, exec, s[10:11]
	v_subrev_u32_e32 v220, 39, v178
	v_sub_u32_e32 v221, 39, v178
	v_max_i32_e32 v221, v220, v221
	v_cmp_gt_u32_e32 vcc, s26, v221
	s_and_saveexec_b64 s[10:11], vcc
	v_med3_i32 v218, v220, s27, 64
	v_lshl_add_u32 v218, v218, 2, v147
	ds_read_b32 v218, v218 offset:256
	s_or_b64 exec, exec, s[10:11]
	v_subrev_u32_e32 v222, 38, v178
	v_sub_u32_e32 v220, 38, v178
	v_max_i32_e32 v220, v222, v220
	v_cmp_gt_u32_e32 vcc, s26, v220
	v_mov_b32_e32 v220, 0xf149f2ca
	v_mov_b32_e32 v221, 0xf149f2ca
	s_and_saveexec_b64 s[10:11], vcc
	v_med3_i32 v221, v222, s27, 64
	v_lshl_add_u32 v221, v221, 2, v147
	ds_read_b32 v221, v221 offset:256
	s_or_b64 exec, exec, s[10:11]
	v_subrev_u32_e32 v222, 37, v178
	v_sub_u32_e32 v178, 37, v178
	v_max_i32_e32 v178, v222, v178
	v_cmp_gt_u32_e32 vcc, s26, v178
	s_and_saveexec_b64 s[10:11], vcc
	v_med3_i32 v178, v222, s27, 64
	v_lshl_add_u32 v178, v178, 2, v147
	ds_read_b32 v220, v178 offset:256
	s_or_b64 exec, exec, s[10:11]
	s_waitcnt lgkmcnt(0)
; template <int D, int NM, int KSTR, int VSTR, bool QLDS, class BF> ...
;     ...
;         float tmax = NEGBIG;
; #pragma unroll
;         for (int i = 0; i < 16; ++i) { S[i] = S[i] * c1 + bias(i); tmax = fmaxf(tmax, S[i]); }
;         tmax = fmaxf(tmax, __shfl_xor(tmax, 32));
;         const float mo = st.m[m], mn = fmaxf(mo, tmax);
;         if (__any(mn > mo)) {
;             const float alpha = __builtin_amdgcn_exp2f(mo - mn);
;             st.l[m] *= alpha;
; #pragma unroll
;             for (int eb = 0; eb < 4; ++eb)
; #pragma unroll
;                 for (int i = 0; i < 16; ++i) st.O[m][eb][i] *= alpha;
;             st.m[m] = mn;
;         }
	v_fmac_f32_e32 v179, 0x3e0293ee, v66
	v_fmac_f32_e32 v177, 0x3e0293ee, v67
	v_max3_f32 v66, v179, s15, v177
	v_fmac_f32_e32 v198, 0x3e0293ee, v68
	v_fmac_f32_e32 v197, 0x3e0293ee, v69
	v_max3_f32 v66, v66, v198, v197
	v_fmac_f32_e32 v200, 0x3e0293ee, v70
	v_fmac_f32_e32 v199, 0x3e0293ee, v71
	v_max3_f32 v66, v66, v200, v199
	v_fmac_f32_e32 v202, 0x3e0293ee, v72
	v_fmac_f32_e32 v201, 0x3e0293ee, v73
	v_max3_f32 v66, v66, v202, v201
	v_fmac_f32_e32 v215, 0x3e0293ee, v74
	v_fmac_f32_e32 v203, 0x3e0293ee, v75
	v_and_b32_e32 v68, 64, v208
	v_max3_f32 v66, v66, v215, v203
	v_fmac_f32_e32 v217, 0x3e0293ee, v76
	v_fmac_f32_e32 v216, 0x3e0293ee, v77
	v_xor_b32_e32 v67, 32, v208
	v_add_u32_e32 v68, 64, v68
	v_max3_f32 v66, v66, v217, v216
	v_fmac_f32_e32 v219, 0x3e0293ee, v78
	v_fmac_f32_e32 v218, 0x3e0293ee, v79
	v_cmp_lt_i32_e32 vcc, v67, v68
	v_max3_f32 v66, v66, v219, v218
	v_fmac_f32_e32 v221, 0x3e0293ee, v80
	v_cndmask_b32_e32 v67, v208, v67, vcc
	v_fmac_f32_e32 v220, 0x3e0293ee, v81
	v_lshlrev_b32_e32 v67, 2, v67
	v_max3_f32 v66, v66, v221, v220
	ds_bpermute_b32 v67, v67, v66
	s_waitcnt lgkmcnt(0)
	v_max3_f32 v66, v193, v66, v67
	v_cmp_gt_f32_e32 vcc, v66, v193
	s_cbranch_vccz .LBB0_208
	v_sub_f32_e32 v67, v193, v66
	v_exp_f32_e32 v68, v67
	v_mov_b32_e32 v193, v66
	v_mul_f32_e32 v194, v194, v68
	v_pk_mul_f32 v[64:65], v[64:65], v[68:69] op_sel_hi:[1,0]
	v_pk_mul_f32 v[62:63], v[62:63], v[68:69] op_sel_hi:[1,0]
	v_pk_mul_f32 v[60:61], v[60:61], v[68:69] op_sel_hi:[1,0]
	v_pk_mul_f32 v[58:59], v[58:59], v[68:69] op_sel_hi:[1,0]
	v_pk_mul_f32 v[56:57], v[56:57], v[68:69] op_sel_hi:[1,0]
	v_pk_mul_f32 v[54:55], v[54:55], v[68:69] op_sel_hi:[1,0]
	v_pk_mul_f32 v[52:53], v[52:53], v[68:69] op_sel_hi:[1,0]
	v_pk_mul_f32 v[50:51], v[50:51], v[68:69] op_sel_hi:[1,0]
	v_pk_mul_f32 v[48:49], v[48:49], v[68:69] op_sel_hi:[1,0]
	v_pk_mul_f32 v[46:47], v[46:47], v[68:69] op_sel_hi:[1,0]
	v_pk_mul_f32 v[44:45], v[44:45], v[68:69] op_sel_hi:[1,0]
	v_pk_mul_f32 v[42:43], v[42:43], v[68:69] op_sel_hi:[1,0]
	v_pk_mul_f32 v[40:41], v[40:41], v[68:69] op_sel_hi:[1,0]
	v_pk_mul_f32 v[38:39], v[38:39], v[68:69] op_sel_hi:[1,0]
	v_pk_mul_f32 v[36:37], v[36:37], v[68:69] op_sel_hi:[1,0]
	v_pk_mul_f32 v[34:35], v[34:35], v[68:69] op_sel_hi:[1,0]
	v_pk_mul_f32 v[32:33], v[32:33], v[68:69] op_sel_hi:[1,0]
	v_pk_mul_f32 v[30:31], v[30:31], v[68:69] op_sel_hi:[1,0]
	v_pk_mul_f32 v[28:29], v[28:29], v[68:69] op_sel_hi:[1,0]
	v_pk_mul_f32 v[26:27], v[26:27], v[68:69] op_sel_hi:[1,0]
	v_pk_mul_f32 v[24:25], v[24:25], v[68:69] op_sel_hi:[1,0]
	v_pk_mul_f32 v[22:23], v[22:23], v[68:69] op_sel_hi:[1,0]
	v_pk_mul_f32 v[20:21], v[20:21], v[68:69] op_sel_hi:[1,0]
	v_pk_mul_f32 v[18:19], v[18:19], v[68:69] op_sel_hi:[1,0]
	v_pk_mul_f32 v[16:17], v[16:17], v[68:69] op_sel_hi:[1,0]
	v_pk_mul_f32 v[14:15], v[14:15], v[68:69] op_sel_hi:[1,0]
	v_pk_mul_f32 v[12:13], v[12:13], v[68:69] op_sel_hi:[1,0]
	v_pk_mul_f32 v[10:11], v[10:11], v[68:69] op_sel_hi:[1,0]
	v_pk_mul_f32 v[8:9], v[8:9], v[68:69] op_sel_hi:[1,0]
	v_pk_mul_f32 v[6:7], v[6:7], v[68:69] op_sel_hi:[1,0]
	v_pk_mul_f32 v[4:5], v[4:5], v[68:69] op_sel_hi:[1,0]
	v_pk_mul_f32 v[2:3], v[2:3], v[68:69] op_sel_hi:[1,0]

; #define LAS __attribute__((address_space(3)))
; #define MFMA32(a, b, c) __builtin_amdgcn_mfma_f32_32x32x16_bf16((a), (b), (c), 0, 0, 0)
; template <int D, int NM, int KSTR, int VSTR, bool QLDS, class BF> ...
;     v8s P[NM][2];
; #pragma unroll
;     for (int m = 0; m < NM; ++m) {
;         const LAS unsigned char* Kb = (m == 0 ? K0 : K1) + (32 * kk + r) * KSTR + h * 16;
;         v16f S;
; #pragma unroll
;         for (int i = 0; i < 16; ++i) S[i] = 0.f;
;         v8s kfa[D / 16];
; #pragma unroll
;         for (int ks = 0; ks < D / 16; ++ks) kfa[ks] = *(const LAS v8s*)(Kb + ks * 32);
;         __builtin_amdgcn_sched_barrier(0);
; #pragma unroll
;         for (int ks = 0; ks < D / 16; ++ks) { const v8s qf = QLDS ? *(const LAS v8s*)(qlds + (m * (D / 16) + ks) * 1024) : Q[m][ks]; S = MFMA32(kfa[ks], qf, S); }
;         __builtin_amdgcn_sched_barrier(0);
;         float tmax = NEGBIG;
; #pragma unroll
;         for (int i = 0; i < 16; ++i) { S[i] = S[i] * c1 + bias(i); tmax = fmaxf(tmax, S[i]); }
; __device__ __forceinline__ void dil_item(const Params& p, LAS unsigned char* lds, const int bitem) {
;     ...
;             for (int kk = 0; kk < 2; ++kk) {
;                 const int js = j0 + 32 * kk;
;                 if (js + 31 >= jq0 - 64 && js <= jq0 + 31 + 64) {
;                     const BiasBand bf{tab, js + 4 * h - jq};
;                     attn_subtile<128, 1, 272, 320, false>(base + DL_K, base + DL_K, base + DL_VT, kk, Q, nullptr, st, c1, bf, r, h);
.LBB0_209:
	s_or_b64 exec, exec, s[20:21]
	v_subrev_u32_e32 v66, 32, v176
	v_add_u32_e32 v67, -1, v176
	v_cmp_ge_i32_e32 vcc, v67, v188
	v_cmp_le_i32_e64 s[38:39], v66, v189
	s_and_b64 s[10:11], vcc, s[38:39]
	s_and_saveexec_b64 s[20:21], s[10:11]
	s_cbranch_execz .LBB0_164
	v_add_u32_e32 v70, v190, v187
	ds_read_b128 v[66:69], v70 offset:8704
	ds_read_b128 v[198:201], v70 offset:8736
	ds_read_b128 v[216:219], v70 offset:8768
	ds_read_b128 v[220:223], v70 offset:8800
	ds_read_b128 v[224:227], v70 offset:8832
	ds_read_b128 v[228:231], v70 offset:8864
	ds_read_b128 v[232:235], v70 offset:8896
	ds_read_b128 v[236:239], v70 offset:8928
	v_lshl_add_u64 v[176:177], v[174:175], 0, s[6:7]
	v_subrev_u32_e32 v179, 32, v176
	s_waitcnt lgkmcnt(7)
	v_mfma_f32_32x32x16_bf16 v[66:81], v[66:69], v[82:85], 0
	s_waitcnt lgkmcnt(6)
	v_mfma_f32_32x32x16_bf16 v[66:81], v[198:201], v[86:89], v[66:81]
	s_waitcnt lgkmcnt(5)
	v_mfma_f32_32x32x16_bf16 v[66:81], v[216:219], v[90:93], v[66:81]
	s_waitcnt lgkmcnt(4)
	v_mfma_f32_32x32x16_bf16 v[66:81], v[220:223], v[94:97], v[66:81]
	s_waitcnt lgkmcnt(3)
	v_mfma_f32_32x32x16_bf16 v[66:81], v[224:227], v[98:101], v[66:81]
	s_waitcnt lgkmcnt(2)
	v_mfma_f32_32x32x16_bf16 v[66:81], v[228:231], v[102:105], v[66:81]
	s_waitcnt lgkmcnt(1)
	v_mfma_f32_32x32x16_bf16 v[66:81], v[232:235], v[106:109], v[66:81]
	s_waitcnt lgkmcnt(0)
	v_mfma_f32_32x32x16_bf16 v[66:81], v[236:239], v[110:113], v[66:81]
	v_sub_u32_e32 v177, 0, v179
	v_max_i32_e32 v177, v179, v177
	v_cmp_gt_u32_e32 vcc, s26, v177
	v_mov_b32_e32 v177, 0xf149f2ca
	v_mov_b32_e32 v178, 0xf149f2ca
	s_and_saveexec_b64 s[10:11], vcc
	v_med3_i32 v178, v179, s27, 64
	v_lshl_add_u32 v178, v178, 2, v147
	ds_read_b32 v178, v178 offset:256
	s_or_b64 exec, exec, s[10:11]
	v_subrev_u32_e32 v179, 31, v176
	v_sub_u32_e32 v197, 31, v176
	v_max_i32_e32 v197, v179, v197
	v_cmp_gt_u32_e32 vcc, s26, v197
	s_and_saveexec_b64 s[10:11], vcc
	v_med3_i32 v177, v179, s27, 64
	v_lshl_add_u32 v177, v177, 2, v147
	ds_read_b32 v177, v177 offset:256
	s_or_b64 exec, exec, s[10:11]
	v_subrev_u32_e32 v198, 30, v176
	v_sub_u32_e32 v179, 30, v176
	v_max_i32_e32 v179, v198, v179
	v_cmp_gt_u32_e32 vcc, s26, v179
	v_mov_b32_e32 v179, 0xf149f2ca
	v_mov_b32_e32 v197, 0xf149f2ca
	s_and_saveexec_b64 s[10:11], vcc
	v_med3_i32 v197, v198, s27, 64
	v_lshl_add_u32 v197, v197, 2, v147
	ds_read_b32 v197, v197 offset:256
	s_or_b64 exec, exec, s[10:11]
	v_subrev_u32_e32 v198, 29, v176
	v_sub_u32_e32 v199, 29, v176
	v_max_i32_e32 v199, v198, v199
	v_cmp_gt_u32_e32 vcc, s26, v199
	s_and_saveexec_b64 s[10:11], vcc
	v_med3_i32 v179, v198, s27, 64
	v_lshl_add_u32 v179, v179, 2, v147
	ds_read_b32 v179, v179 offset:256
	s_or_b64 exec, exec, s[10:11]
	v_subrev_u32_e32 v200, 24, v176
	v_sub_u32_e32 v198, 24, v176
	v_max_i32_e32 v198, v200, v198
	v_cmp_gt_u32_e32 vcc, s26, v198
	v_mov_b32_e32 v198, 0xf149f2ca
	v_mov_b32_e32 v199, 0xf149f2ca
	s_and_saveexec_b64 s[10:11], vcc
	v_med3_i32 v199, v200, s27, 64
	v_lshl_add_u32 v199, v199, 2, v147
	ds_read_b32 v199, v199 offset:256
	s_or_b64 exec, exec, s[10:11]
	v_subrev_u32_e32 v200, 23, v176
	v_sub_u32_e32 v201, 23, v176
	v_max_i32_e32 v201, v200, v201
	v_cmp_gt_u32_e32 vcc, s26, v201
	s_and_saveexec_b64 s[10:11], vcc
	v_med3_i32 v198, v200, s27, 64
	v_lshl_add_u32 v198, v198, 2, v147
	ds_read_b32 v198, v198 offset:256
	s_or_b64 exec, exec, s[10:11]
	v_subrev_u32_e32 v202, 22, v176
	v_sub_u32_e32 v200, 22, v176
	v_max_i32_e32 v200, v202, v200
	v_cmp_gt_u32_e32 vcc, s26, v200
	v_mov_b32_e32 v200, 0xf149f2ca
	v_mov_b32_e32 v201, 0xf149f2ca
	s_and_saveexec_b64 s[10:11], vcc
	v_med3_i32 v201, v202, s27, 64
	v_lshl_add_u32 v201, v201, 2, v147
	ds_read_b32 v201, v201 offset:256
	s_or_b64 exec, exec, s[10:11]
	v_subrev_u32_e32 v202, 21, v176
	v_sub_u32_e32 v203, 21, v176
	v_max_i32_e32 v203, v202, v203
	v_cmp_gt_u32_e32 vcc, s26, v203
	s_and_saveexec_b64 s[10:11], vcc
	v_med3_i32 v200, v202, s27, 64
	v_lshl_add_u32 v200, v200, 2, v147
	ds_read_b32 v200, v200 offset:256
	s_or_b64 exec, exec, s[10:11]
	v_add_u32_e32 v215, -16, v176
	v_sub_u32_e32 v202, 16, v176
	v_max_i32_e32 v202, v215, v202
	v_cmp_gt_u32_e32 vcc, s26, v202
	v_mov_b32_e32 v202, 0xf149f2ca
	v_mov_b32_e32 v203, 0xf149f2ca
	s_and_saveexec_b64 s[10:11], vcc
	v_med3_i32 v203, v215, s27, 64
	v_lshl_add_u32 v203, v203, 2, v147
	ds_read_b32 v203, v203 offset:256
	s_or_b64 exec, exec, s[10:11]
	v_add_u32_e32 v215, -15, v176
	v_sub_u32_e32 v216, 15, v176
	v_max_i32_e32 v216, v215, v216
	v_cmp_gt_u32_e32 vcc, s26, v216
	s_and_saveexec_b64 s[10:11], vcc
	v_med3_i32 v202, v215, s27, 64
	v_lshl_add_u32 v202, v202, 2, v147
	ds_read_b32 v202, v202 offset:256
	s_or_b64 exec, exec, s[10:11]
	v_add_u32_e32 v217, -14, v176
	v_sub_u32_e32 v215, 14, v176
	v_max_i32_e32 v215, v217, v215
	v_cmp_gt_u32_e32 vcc, s26, v215
	v_mov_b32_e32 v215, 0xf149f2ca
	v_mov_b32_e32 v216, 0xf149f2ca
	s_and_saveexec_b64 s[10:11], vcc
	v_med3_i32 v216, v217, s27, 64
	v_lshl_add_u32 v216, v216, 2, v147
	ds_read_b32 v216, v216 offset:256
	s_or_b64 exec, exec, s[10:11]
	v_add_u32_e32 v217, -13, v176
	v_sub_u32_e32 v218, 13, v176
	v_max_i32_e32 v218, v217, v218
	v_cmp_gt_u32_e32 vcc, s26, v218
	s_and_saveexec_b64 s[10:11], vcc
	v_med3_i32 v215, v217, s27, 64
	v_lshl_add_u32 v215, v215, 2, v147
	ds_read_b32 v215, v215 offset:256
	s_or_b64 exec, exec, s[10:11]
	v_add_u32_e32 v219, -8, v176
	v_sub_u32_e32 v217, 8, v176
	v_max_i32_e32 v217, v219, v217
	v_cmp_gt_u32_e32 vcc, s26, v217
	v_mov_b32_e32 v217, 0xf149f2ca
	v_mov_b32_e32 v218, 0xf149f2ca
	s_and_saveexec_b64 s[10:11], vcc
	v_med3_i32 v218, v219, s27, 64
	v_lshl_add_u32 v218, v218, 2, v147
	ds_read_b32 v218, v218 offset:256
	s_or_b64 exec, exec, s[10:11]
	v_add_u32_e32 v219, -7, v176
	v_sub_u32_e32 v220, 7, v176
	v_max_i32_e32 v220, v219, v220
	v_cmp_gt_u32_e32 vcc, s26, v220
	s_and_saveexec_b64 s[10:11], vcc
	v_med3_i32 v217, v219, s27, 64
	v_lshl_add_u32 v217, v217, 2, v147
	ds_read_b32 v217, v217 offset:256
	s_or_b64 exec, exec, s[10:11]
	v_add_u32_e32 v221, -6, v176
	v_sub_u32_e32 v219, 6, v176
	v_max_i32_e32 v219, v221, v219
	v_cmp_gt_u32_e32 vcc, s26, v219
	v_mov_b32_e32 v219, 0xf149f2ca
	v_mov_b32_e32 v220, 0xf149f2ca
	s_and_saveexec_b64 s[10:11], vcc
	v_med3_i32 v220, v221, s27, 64
	v_lshl_add_u32 v220, v220, 2, v147
	ds_read_b32 v220, v220 offset:256
	s_or_b64 exec, exec, s[10:11]
	v_add_u32_e32 v221, -5, v176
	v_sub_u32_e32 v176, 5, v176
	v_max_i32_e32 v176, v221, v176
	v_cmp_gt_u32_e32 vcc, s26, v176
	s_and_saveexec_b64 s[10:11], vcc
	v_med3_i32 v176, v221, s27, 64
	v_lshl_add_u32 v176, v176, 2, v147
	ds_read_b32 v219, v176 offset:256
	s_or_b64 exec, exec, s[10:11]
	s_waitcnt lgkmcnt(0)
; template <int D, int NM, int KSTR, int VSTR, bool QLDS, class BF> ...
;     ...
;         float tmax = NEGBIG;
; #pragma unroll
;         for (int i = 0; i < 16; ++i) { S[i] = S[i] * c1 + bias(i); tmax = fmaxf(tmax, S[i]); }
;         tmax = fmaxf(tmax, __shfl_xor(tmax, 32));
;         const float mo = st.m[m], mn = fmaxf(mo, tmax);
;         if (__any(mn > mo)) {
;             const float alpha = __builtin_amdgcn_exp2f(mo - mn);
;             st.l[m] *= alpha;
; #pragma unroll
;             for (int eb = 0; eb < 4; ++eb)
; #pragma unroll
;                 for (int i = 0; i < 16; ++i) st.O[m][eb][i] *= alpha;
;             st.m[m] = mn;
;         }
	v_fmac_f32_e32 v178, 0x3e0293ee, v66
	v_fmac_f32_e32 v177, 0x3e0293ee, v67
	v_max3_f32 v66, v178, s15, v177
	v_fmac_f32_e32 v197, 0x3e0293ee, v68
	v_fmac_f32_e32 v179, 0x3e0293ee, v69
	v_max3_f32 v66, v66, v197, v179
	v_fmac_f32_e32 v199, 0x3e0293ee, v70
	v_fmac_f32_e32 v198, 0x3e0293ee, v71
	v_max3_f32 v66, v66, v199, v198
	v_fmac_f32_e32 v201, 0x3e0293ee, v72
	v_fmac_f32_e32 v200, 0x3e0293ee, v73
	v_max3_f32 v66, v66, v201, v200
	v_fmac_f32_e32 v203, 0x3e0293ee, v74
	v_fmac_f32_e32 v202, 0x3e0293ee, v75
	v_and_b32_e32 v68, 64, v208
	v_max3_f32 v66, v66, v203, v202
	v_fmac_f32_e32 v216, 0x3e0293ee, v76
	v_fmac_f32_e32 v215, 0x3e0293ee, v77
	v_xor_b32_e32 v67, 32, v208
	v_add_u32_e32 v68, 64, v68
	v_max3_f32 v66, v66, v216, v215
	v_fmac_f32_e32 v218, 0x3e0293ee, v78
	v_fmac_f32_e32 v217, 0x3e0293ee, v79
	v_cmp_lt_i32_e32 vcc, v67, v68
	v_max3_f32 v66, v66, v218, v217
	v_fmac_f32_e32 v220, 0x3e0293ee, v80
	v_cndmask_b32_e32 v67, v208, v67, vcc
	v_fmac_f32_e32 v219, 0x3e0293ee, v81
	v_lshlrev_b32_e32 v67, 2, v67
	v_max3_f32 v66, v66, v220, v219
	ds_bpermute_b32 v67, v67, v66
	s_waitcnt lgkmcnt(0)
	v_max3_f32 v66, v193, v66, v67
	v_cmp_gt_f32_e32 vcc, v66, v193
	s_cbranch_vccz .LBB0_163
	v_sub_f32_e32 v67, v193, v66
	v_exp_f32_e32 v68, v67
	v_mov_b32_e32 v193, v66
	v_mul_f32_e32 v194, v194, v68
	v_pk_mul_f32 v[64:65], v[64:65], v[68:69] op_sel_hi:[1,0]
	v_pk_mul_f32 v[62:63], v[62:63], v[68:69] op_sel_hi:[1,0]
	v_pk_mul_f32 v[60:61], v[60:61], v[68:69] op_sel_hi:[1,0]
	v_pk_mul_f32 v[58:59], v[58:59], v[68:69] op_sel_hi:[1,0]
	v_pk_mul_f32 v[56:57], v[56:57], v[68:69] op_sel_hi:[1,0]
	v_pk_mul_f32 v[54:55], v[54:55], v[68:69] op_sel_hi:[1,0]
	v_pk_mul_f32 v[52:53], v[52:53], v[68:69] op_sel_hi:[1,0]
	v_pk_mul_f32 v[50:51], v[50:51], v[68:69] op_sel_hi:[1,0]
	v_pk_mul_f32 v[48:49], v[48:49], v[68:69] op_sel_hi:[1,0]
	v_pk_mul_f32 v[46:47], v[46:47], v[68:69] op_sel_hi:[1,0]
	v_pk_mul_f32 v[44:45], v[44:45], v[68:69] op_sel_hi:[1,0]
	v_pk_mul_f32 v[42:43], v[42:43], v[68:69] op_sel_hi:[1,0]
	v_pk_mul_f32 v[40:41], v[40:41], v[68:69] op_sel_hi:[1,0]
	v_pk_mul_f32 v[38:39], v[38:39], v[68:69] op_sel_hi:[1,0]
	v_pk_mul_f32 v[36:37], v[36:37], v[68:69] op_sel_hi:[1,0]
	v_pk_mul_f32 v[34:35], v[34:35], v[68:69] op_sel_hi:[1,0]
	v_pk_mul_f32 v[32:33], v[32:33], v[68:69] op_sel_hi:[1,0]
	v_pk_mul_f32 v[30:31], v[30:31], v[68:69] op_sel_hi:[1,0]
	v_pk_mul_f32 v[28:29], v[28:29], v[68:69] op_sel_hi:[1,0]
	v_pk_mul_f32 v[26:27], v[26:27], v[68:69] op_sel_hi:[1,0]
	v_pk_mul_f32 v[24:25], v[24:25], v[68:69] op_sel_hi:[1,0]
	v_pk_mul_f32 v[22:23], v[22:23], v[68:69] op_sel_hi:[1,0]
	v_pk_mul_f32 v[20:21], v[20:21], v[68:69] op_sel_hi:[1,0]
	v_pk_mul_f32 v[18:19], v[18:19], v[68:69] op_sel_hi:[1,0]
	v_pk_mul_f32 v[16:17], v[16:17], v[68:69] op_sel_hi:[1,0]
	v_pk_mul_f32 v[14:15], v[14:15], v[68:69] op_sel_hi:[1,0]
	v_pk_mul_f32 v[12:13], v[12:13], v[68:69] op_sel_hi:[1,0]
	v_pk_mul_f32 v[10:11], v[10:11], v[68:69] op_sel_hi:[1,0]
	v_pk_mul_f32 v[8:9], v[8:9], v[68:69] op_sel_hi:[1,0]
	v_pk_mul_f32 v[6:7], v[6:7], v[68:69] op_sel_hi:[1,0]
	v_pk_mul_f32 v[4:5], v[4:5], v[68:69] op_sel_hi:[1,0]
	v_pk_mul_f32 v[2:3], v[2:3], v[68:69] op_sel_hi:[1,0]
	s_branch .LBB0_163
